# seams 10-13 as XCD-group-local barriers (no L2 write-back; flag-guarded fall-back to the grid barrier) + row phases 11/14 own the rows of their GEMM group
# speedup vs baseline: 1.0066x; 1.0066x over previous
; #define LAS __attribute__((address_space(3)))
; __device__ __forceinline__ unsigned xb_add(unsigned* p, unsigned v) { return __hip_atomic_fetch_add(p, v, __ATOMIC_RELAXED, __HIP_MEMORY_SCOPE_AGENT); }
; __device__ __forceinline__ unsigned xb_xcc_id() { return (unsigned)__builtin_amdgcn_s_getreg((3 << 11) | 20) & 0xFu; }
; __device__ __forceinline__ XcdBarrier xcd_barrier_post(unsigned* bar, volatile LAS unsigned* st) {
;     XcdBarrier b; b.bar = bar; b.x = xb_xcc_id(); b.st = st;
;     if (threadIdx.x == 0) (void)xb_add(&bar[XB_XCNT(b.x)], 1u);
;     return b;
; }
; __global__ void __launch_bounds__(NTHR, 2) fwd_megakernel(KArgs a) {
;     extern __shared__ __attribute__((aligned(16))) unsigned char lds_raw[];
;     LAS unsigned char* lds = (LAS unsigned char*)lds_raw;
;     __builtin_assume(__builtin_amdgcn_workitem_id_y() == 0); __builtin_assume(__builtin_amdgcn_workitem_id_z() == 0);
;     cg::grid_group grid = cg::this_grid();
;     const int tid = threadIdx.x, lane = tid & 63, wave = __builtin_amdgcn_readfirstlane(tid >> 6);
;     unsigned char* ws = a.ws;
;     const int lo = a.ph_lo, hi = a.ph_hi;
;     const float* mods0 = (const float*)(ws + WS_MODS); const float* mods1 = mods0 + 3 * MODW;
;     bf16r* AY = (bf16r*)(ws + WS_AY); bf16r* HB = (bf16r*)(ws + WS_H);
;     volatile LAS unsigned* MISC = (volatile LAS unsigned*)(lds + RING_BYTES + 64);
;     if (tid < 2) MISC[tid] = 0u;
;     __syncthreads();
;     XcdBarrier bar = xcd_barrier_post((unsigned*)(ws + WS_CTL) + 4096, MISC);
_Z14fwd_megakernel5KArgs:
	s_mov_b32 s14, s2
	s_load_dwordx8 s[52:59], s[0:1], 0x80
	s_load_dwordx4 s[92:95], s[0:1], 0xa0
	s_load_dword s2, s[0:1], 0xb0
	s_add_u32 s4, s0, 0xa8
	s_addc_u32 s5, s1, 0
	v_readfirstlane_b32 s86, v0
	v_cmp_gt_u32_e32 vcc, 2, v0
	s_waitcnt lgkmcnt(0)
	v_writelane_b32 v254, s2, 0
	s_and_saveexec_b64 s[2:3], vcc
	v_lshl_add_u32 v1, v0, 2, 0
	v_add_u32_e32 v1, 0x20040, v1
	v_mov_b32_e32 v2, 0
	ds_write_b32 v1, v2
	s_or_b64 exec, exec, s[2:3]
	s_add_u32 s2, s58, 0x4000
	s_addc_u32 s3, s59, 0
	v_writelane_b32 v254, s2, 1
	s_waitcnt lgkmcnt(0)
	s_barrier
	v_writelane_b32 v254, s3, 2
	s_getreg_b32 s2, hwreg(HW_REG_XCC_ID, 0, 4)
	s_and_b32 s2, s2, 15
	v_writelane_b32 v254, s2, 3
	s_and_b32 s6, s14, 7
	s_cmp_eq_u32 s6, s2
	s_cbranch_scc1 .Lxl_same
	v_mov_b32_e32 v1, 0
	v_mov_b32_e32 v2, 1
	s_add_u32 s6, s58, 0x11000
	s_addc_u32 s7, s59, 0
	global_store_dword v1, v2, s[6:7]
.Lxl_same:
	v_cmp_eq_u32_e64 s[6:7], 0, v0
	s_mov_b64 s[2:3], exec
	s_nop 0
	v_writelane_b32 v254, s6, 4
	s_nop 1
	v_writelane_b32 v254, s7, 5
	s_and_b64 s[6:7], s[2:3], s[6:7]
	s_mov_b64 exec, s[6:7]
	s_cbranch_execz .LBB0_5
	s_mov_b64 s[6:7], exec
	v_mbcnt_lo_u32_b32 v1, s6, 0
	v_mbcnt_hi_u32_b32 v1, s7, v1
	v_cmp_eq_u32_e32 vcc, 0, v1
	s_and_b64 s[8:9], exec, vcc
	s_mov_b64 exec, s[8:9]
	s_cbranch_execz .LBB0_5
	v_readlane_b32 s8, v254, 3
	s_bcnt1_i32_b64 s6, s[6:7]
	s_lshl_b32 s8, s8, 8
	v_mov_b32_e32 v2, s6
	v_readlane_b32 s6, v254, 1
	v_mov_b32_e32 v1, s8
	v_readlane_b32 s7, v254, 2
	s_nop 4
	global_atomic_add v1, v2, s[6:7] offset:1024

; __device__ __forceinline__ unsigned xb_ld(unsigned* p)              { return __hip_atomic_load(p, __ATOMIC_RELAXED, __HIP_MEMORY_SCOPE_AGENT); }
; __device__ __forceinline__ unsigned xb_add(unsigned* p, unsigned v) { return __hip_atomic_fetch_add(p, v, __ATOMIC_RELAXED, __HIP_MEMORY_SCOPE_AGENT); }
; #define XB_SPIN(cond, bar) do { unsigned _sp = 0; while (cond) { __builtin_amdgcn_s_sleep(1); \
;     if ((++_sp & 255u) == 0u) { if (xb_ld(&(bar)[XB_TMO])) break; if (_sp > XB_SPIN_CAP) { atomicAdd(&(bar)[XB_TMO], 1u); break; } } } } while (0)
; __device__ __forceinline__ void xcd_barrier(const XcdBarrier& b) {
;     asm volatile("s_waitcnt vmcnt(0)" ::: "memory");
;     __syncthreads();
;     if (threadIdx.x == 0) {
;         unsigned* bar = b.bar;
;         __builtin_amdgcn_s_waitcnt(0);
;         unsigned nloc = b.st[0], nx = b.st[1];
;         if (nloc == 0u) { xcd_barrier_complete(bar, b.x, nloc, nx); b.st[0] = nloc; b.st[1] = nx; }
;         const unsigned old = xb_add(&bar[XB_XSUB(b.x)], 1u);
;         const unsigned gen = old / nloc;
;         if (old + 1u == (gen + 1u) * nloc) {
;             __builtin_amdgcn_fence(__ATOMIC_RELEASE, "agent");
;             asm volatile("s_waitcnt vmcnt(0)" ::: "memory");
;             const unsigned og = xb_add(&bar[XB_TOP], 1u);
;             const unsigned tg = og / nx;
;             if (og + 1u == (tg + 1u) * nx) xb_add(&bar[XB_TOPGEN], 1u);
;             else XB_SPIN(xb_ld(&bar[XB_TOPGEN]) == tg, bar);
;             __builtin_amdgcn_fence(__ATOMIC_ACQUIRE, "agent");
;             xb_add(&bar[XB_XGEN(b.x)], 1u);
;             asm volatile("s_waitcnt vmcnt(0)" ::: "memory");
;         } else {
;             XB_SPIN(xb_ld(&bar[XB_XGEN(b.x)]) == gen, bar);
;             __builtin_amdgcn_fence(__ATOMIC_ACQUIRE, "agent");
;             asm volatile("s_waitcnt vmcnt(0)" ::: "memory");
;         }
;     }
;     __syncthreads();
; }
.LBB0_906:
	s_cmp_gt_i32 s93, 11
	s_cselect_b64 s[0:1], -1, 0
	s_and_b64 s[2:3], s[4:5], s[0:1]
	s_andn2_b64 vcc, exec, s[2:3]
	s_cbranch_vccnz .LBB0_960
	s_waitcnt vmcnt(0) lgkmcnt(0)
	s_barrier
	v_mov_b32_e32 v1, 0
	s_add_u32 s6, s58, 0x11000
	s_addc_u32 s7, s59, 0
	global_load_dword v1, v1, s[6:7] sc1
	s_mov_b32 s99, 0
	s_waitcnt vmcnt(0)
	v_readfirstlane_b32 s100, v1
	s_cmp_lg_u32 s100, 0
	s_cbranch_scc1 .Lxl10_full
	s_and_b32 s6, s14, 7
	s_sub_u32 s7, s94, s6
	s_add_u32 s7, s7, 7
	s_lshr_b32 s7, s7, 3
	s_add_u32 s99, s99, s7
	s_lshl_b32 s6, s6, 8
	s_add_u32 s6, s6, 0x10000
	s_add_u32 s6, s58, s6
	s_addc_u32 s7, s59, 0
	v_readlane_b32 s4, v254, 4
	v_readlane_b32 s5, v254, 5
	s_and_saveexec_b64 s[2:3], s[4:5]
	s_cbranch_execz .Lxl10_join
	v_mov_b32_e32 v1, 0
	v_mov_b32_e32 v2, 1
	global_atomic_add v1, v2, s[6:7]
	s_mov_b32 s8, 0
.Lxl10_spin:
	global_load_dword v3, v1, s[6:7] sc1
	s_waitcnt vmcnt(0)
	v_readfirstlane_b32 s9, v3
	s_cmp_ge_u32 s9, s99
	s_cbranch_scc1 .Lxl10_done
	s_sleep 1
	s_add_u32 s8, s8, 1
	s_cmp_lt_u32 s8, 0x4000
	s_cbranch_scc1 .Lxl10_spin
.Lxl10_done:
	buffer_inv sc1
	s_waitcnt vmcnt(0)
.Lxl10_join:
	s_or_b64 exec, exec, s[2:3]
	s_barrier
	s_branch .LBB0_960
.Lxl10_full:
	s_waitcnt vmcnt(0)
	s_waitcnt vmcnt(0)
	s_barrier
	s_mov_b64 s[2:3], exec
	v_readlane_b32 s4, v254, 4
	v_readlane_b32 s5, v254, 5
	s_and_b64 s[4:5], s[2:3], s[4:5]
	s_mov_b64 exec, s[4:5]
	s_cbranch_execz .LBB0_959
	s_add_i32 s4, 0, 0x20040
	v_mov_b32_e32 v1, s4
	s_waitcnt vmcnt(0) expcnt(0) lgkmcnt(0)
	ds_read_b32 v3, v1
	s_add_i32 s4, 0, 0x20044
	v_mov_b32_e32 v1, s4
	ds_read_b32 v1, v1
	s_waitcnt lgkmcnt(1)
	v_cmp_ne_u32_e32 vcc, 0, v3
	s_cbranch_vccnz .LBB0_923
	v_readlane_b32 s4, v254, 0
	s_mul_i32 s12, s95, s4
	s_add_u32 s4, s58, 0x4200
	s_addc_u32 s5, s59, 0
	s_add_u32 s6, s58, 0x4400
	s_addc_u32 s7, s59, 0
	s_add_u32 s8, s58, 0x4500
	s_addc_u32 s9, s59, 0
	s_add_u32 s10, s58, 0x4600
	s_addc_u32 s11, s59, 0
	s_add_u32 s24, s58, 0x4700
	s_addc_u32 s25, s59, 0
	s_add_u32 s26, s58, 0x4800
	s_addc_u32 s27, s59, 0
	s_add_u32 s28, s58, 0x4900
	s_addc_u32 s29, s59, 0
	s_add_u32 s30, s58, 0x4a00
	s_addc_u32 s31, s59, 0
	s_add_u32 s36, s58, 0x4b00
	s_addc_u32 s37, s59, 0
	s_add_u32 s38, s58, 0x4c00
	s_addc_u32 s39, s59, 0
	s_add_u32 s40, s58, 0x4d00
	s_addc_u32 s41, s59, 0
	s_add_u32 s42, s58, 0x4e00
	s_addc_u32 s43, s59, 0
	s_add_u32 s44, s58, 0x4f00
	s_addc_u32 s45, s59, 0
	s_add_u32 s46, s58, 0x5000
	s_addc_u32 s47, s59, 0
	s_add_u32 s48, s58, 0x5100
	s_addc_u32 s49, s59, 0
	s_add_u32 s52, s58, 0x5200
	s_addc_u32 s53, s59, 0
	s_add_u32 s54, s58, 0x5300
	s_mul_i32 s12, s12, s94
	s_addc_u32 s55, s59, 0
	s_mov_b32 s13, 1
	v_mov_b32_e32 v17, 0
	s_branch .LBB0_911

; template <bool FIRST, bool HAS_NEXT, bool CTXSPLIT = false>
; __device__ __forceinline__ void phase_rows(const KArgs& a, int row_begin, int nrows, int CH, const float* mods_cur, int gate_ch, const float* g_post, const float* mods_nxt, int sh_ch, const float* g_pre, int lane, int wave) {
;     ...
;     const int gw = blockIdx.x * NWAVES + wave, NGW = gridDim.x * NWAVES;
;     ...
;     for (int ch = gw; ch < nrows / CH; ch += NGW) {
;         const int r0 = row_begin + ch * CH; const int ms = r0 < MLAT ? r0 / SEQ : 2;
;         f32x4 gg[4], gs[4], sh[4];
; #pragma unroll
;         for (int j = 0; j < 4; ++j) { const int col = RCOL(j);
;             gg[j] = *(const f32x4*)(mods_cur + ms * MODW + gate_ch * DM + col) * *(const f32x4*)(g_post + col);
;             if (HAS_NEXT) { gs[j] = *(const f32x4*)(g_pre + col) * (1.0f + *(const f32x4*)(mods_nxt + ms * MODW + (sh_ch + 1) * DM + col)); sh[j] = *(const f32x4*)(mods_nxt + ms * MODW + sh_ch * DM + col); }
;         }
.LBB0_960:
	s_cmp_lt_i32 s92, 12
	s_cselect_b64 s[2:3], -1, 0
	s_and_b64 s[4:5], s[2:3], s[0:1]
	s_andn2_b64 vcc, exec, s[4:5]
	s_cbranch_vccnz .LBB0_966
	s_and_b32 s98, s14, 7
	s_lshl_b32 s98, s98, 5
	s_lshr_b32 s101, s14, 3
	s_or_b32 s98, s98, s101
	s_lshl_b32 s0, s98, 3
	v_readlane_b32 s1, v254, 6
	s_add_i32 s24, s1, s0
	s_cmpk_gt_i32 s24, 0x7ff
	s_cbranch_scc1 .LBB0_966
	v_mbcnt_lo_u32_b32 v1, -1, 0
	v_mbcnt_hi_u32_b32 v3, -1, v1
	v_and_b32_e32 v1, 64, v3
	v_add_u32_e32 v5, 64, v1
	v_xor_b32_e32 v1, 1, v3
	v_cmp_lt_i32_e32 vcc, v1, v5
	v_xor_b32_e32 v6, 2, v3
	s_lshl_b32 s25, s94, 3
	v_cndmask_b32_e32 v1, v3, v1, vcc
	v_cmp_lt_i32_e32 vcc, v6, v5
	s_add_u32 s0, s16, 0x1000
	s_addc_u32 s1, s17, 0
	v_cndmask_b32_e32 v6, v3, v6, vcc
	v_lshlrev_b32_e32 v68, 2, v6
	v_xor_b32_e32 v6, 4, v3
	v_cmp_lt_i32_e32 vcc, v6, v5
	s_add_u32 s2, s50, 0x1000
	v_lshlrev_b32_e32 v2, 3, v198
	v_cndmask_b32_e32 v6, v3, v6, vcc
	v_lshlrev_b32_e32 v69, 2, v6
	v_xor_b32_e32 v6, 8, v3
	v_cmp_lt_i32_e32 vcc, v6, v5
	s_addc_u32 s3, s51, 0
	v_mov_b32_e32 v19, 0
	v_cndmask_b32_e32 v6, v3, v6, vcc
	v_lshlrev_b32_e32 v70, 2, v6
	v_xor_b32_e32 v6, 16, v3
	v_lshlrev_b32_e32 v18, 5, v198
	v_or_b32_e32 v4, 0x200, v2
	v_cmp_lt_i32_e32 vcc, v6, v5
	v_lshl_add_u64 v[20:21], s[2:3], 0, v[18:19]
	v_lshl_add_u64 v[22:23], s[0:1], 0, v[18:19]
	v_lshlrev_b32_e32 v18, 2, v4
	v_cndmask_b32_e32 v6, v3, v6, vcc
	v_lshl_add_u64 v[26:27], s[0:1], 0, v[18:19]
	v_lshlrev_b32_e32 v71, 2, v6
	v_xor_b32_e32 v6, 32, v3
	v_readlane_b32 s1, v254, 6
	v_cmp_lt_i32_e32 vcc, v6, v5
	s_lshl_b32 s0, s98, 6
	s_lshl_b32 s1, s1, 3
	v_cndmask_b32_e32 v3, v3, v6, vcc
	s_add_i32 s6, s0, s1
	v_lshl_add_u64 v[24:25], s[2:3], 0, v[18:19]
	v_lshlrev_b32_e32 v1, 2, v1
	v_lshlrev_b32_e32 v72, 2, v3
	v_lshlrev_b32_e32 v18, 4, v198
	s_lshl_b32 s26, s94, 6
	s_or_b32 s8, s6, 1
	v_lshlrev_b32_e32 v73, 2, v2
	v_lshlrev_b32_e32 v74, 2, v4
	s_mov_b32 s27, 0xd000000
	s_mov_b32 s28, 0x2a00000
	v_mov_b32_e32 v75, 0x358637bd
	s_mov_b32 s29, 0xf800000
	v_mov_b32_e32 v76, 0x260

; __device__ __forceinline__ unsigned xb_ld(unsigned* p)              { return __hip_atomic_load(p, __ATOMIC_RELAXED, __HIP_MEMORY_SCOPE_AGENT); }
; __device__ __forceinline__ unsigned xb_add(unsigned* p, unsigned v) { return __hip_atomic_fetch_add(p, v, __ATOMIC_RELAXED, __HIP_MEMORY_SCOPE_AGENT); }
; #define XB_SPIN(cond, bar) do { unsigned _sp = 0; while (cond) { __builtin_amdgcn_s_sleep(1); \
;     if ((++_sp & 255u) == 0u) { if (xb_ld(&(bar)[XB_TMO])) break; if (_sp > XB_SPIN_CAP) { atomicAdd(&(bar)[XB_TMO], 1u); break; } } } } while (0)
; __device__ __forceinline__ void xcd_barrier(const XcdBarrier& b) {
;     asm volatile("s_waitcnt vmcnt(0)" ::: "memory");
;     __syncthreads();
;     if (threadIdx.x == 0) {
;         unsigned* bar = b.bar;
;         __builtin_amdgcn_s_waitcnt(0);
;         unsigned nloc = b.st[0], nx = b.st[1];
;         if (nloc == 0u) { xcd_barrier_complete(bar, b.x, nloc, nx); b.st[0] = nloc; b.st[1] = nx; }
;         const unsigned old = xb_add(&bar[XB_XSUB(b.x)], 1u);
;         const unsigned gen = old / nloc;
;         if (old + 1u == (gen + 1u) * nloc) {
;             __builtin_amdgcn_fence(__ATOMIC_RELEASE, "agent");
;             asm volatile("s_waitcnt vmcnt(0)" ::: "memory");
;             const unsigned og = xb_add(&bar[XB_TOP], 1u);
;             const unsigned tg = og / nx;
;             if (og + 1u == (tg + 1u) * nx) xb_add(&bar[XB_TOPGEN], 1u);
;             else XB_SPIN(xb_ld(&bar[XB_TOPGEN]) == tg, bar);
;             __builtin_amdgcn_fence(__ATOMIC_ACQUIRE, "agent");
;             xb_add(&bar[XB_XGEN(b.x)], 1u);
;             asm volatile("s_waitcnt vmcnt(0)" ::: "memory");
;         } else {
;             XB_SPIN(xb_ld(&bar[XB_XGEN(b.x)]) == gen, bar);
;             __builtin_amdgcn_fence(__ATOMIC_ACQUIRE, "agent");
;             asm volatile("s_waitcnt vmcnt(0)" ::: "memory");
;         }
;     }
;     __syncthreads();
; }
.LBB0_966:
	s_cmp_gt_i32 s93, 12
	s_cselect_b64 s[0:1], -1, 0
	s_and_b64 s[2:3], s[4:5], s[0:1]
	s_andn2_b64 vcc, exec, s[2:3]
	s_cbranch_vccnz .LBB0_1020
	s_waitcnt vmcnt(0) lgkmcnt(0)
	s_barrier
	s_cmp_lg_u32 s100, 0
	s_cbranch_scc1 .Lxl11_full
	s_and_b32 s6, s14, 7
	s_sub_u32 s7, s94, s6
	s_add_u32 s7, s7, 7
	s_lshr_b32 s7, s7, 3
	s_add_u32 s99, s99, s7
	s_lshl_b32 s6, s6, 8
	s_add_u32 s6, s6, 0x10000
	s_add_u32 s6, s58, s6
	s_addc_u32 s7, s59, 0
	v_readlane_b32 s4, v254, 4
	v_readlane_b32 s5, v254, 5
	s_and_saveexec_b64 s[2:3], s[4:5]
	s_cbranch_execz .Lxl11_join
	v_mov_b32_e32 v1, 0
	v_mov_b32_e32 v2, 1
	global_atomic_add v1, v2, s[6:7]
	s_mov_b32 s8, 0

; __device__ __forceinline__ unsigned xb_add(unsigned* p, unsigned v) { return __hip_atomic_fetch_add(p, v, __ATOMIC_RELAXED, __HIP_MEMORY_SCOPE_AGENT); }
; __device__ __forceinline__ void xcd_barrier(const XcdBarrier& b) {
;     asm volatile("s_waitcnt vmcnt(0)" ::: "memory");
;     __syncthreads();
;     if (threadIdx.x == 0) {
;         unsigned* bar = b.bar;
;         __builtin_amdgcn_s_waitcnt(0);
;         unsigned nloc = b.st[0], nx = b.st[1];
;         if (nloc == 0u) { xcd_barrier_complete(bar, b.x, nloc, nx); b.st[0] = nloc; b.st[1] = nx; }
;         const unsigned old = xb_add(&bar[XB_XSUB(b.x)], 1u);
;         const unsigned gen = old / nloc;
;         if (old + 1u == (gen + 1u) * nloc) {
.Lxl11_full:
	s_waitcnt vmcnt(0)
	s_waitcnt vmcnt(0)
	s_barrier
	s_mov_b64 s[2:3], exec
	v_readlane_b32 s4, v254, 4
	v_readlane_b32 s5, v254, 5
	s_and_b64 s[4:5], s[2:3], s[4:5]
	s_mov_b64 exec, s[4:5]
	s_cbranch_execz .LBB0_1019
	s_add_i32 s4, 0, 0x20040
	v_mov_b32_e32 v1, s4
	s_waitcnt vmcnt(0) expcnt(0) lgkmcnt(0)
	ds_read_b32 v3, v1
	s_add_i32 s4, 0, 0x20044
	v_mov_b32_e32 v1, s4
	ds_read_b32 v1, v1
	s_waitcnt lgkmcnt(1)
	v_cmp_ne_u32_e32 vcc, 0, v3
	s_cbranch_vccnz .LBB0_983
	v_readlane_b32 s4, v254, 0
	s_mul_i32 s12, s95, s4
	s_add_u32 s4, s58, 0x4200
	s_addc_u32 s5, s59, 0
	s_add_u32 s6, s58, 0x4400
	s_addc_u32 s7, s59, 0
	s_add_u32 s8, s58, 0x4500
	s_addc_u32 s9, s59, 0
	s_add_u32 s10, s58, 0x4600
	s_addc_u32 s11, s59, 0
	s_add_u32 s16, s58, 0x4700
	s_addc_u32 s17, s59, 0
	s_add_u32 s24, s58, 0x4800
	s_addc_u32 s25, s59, 0
	s_add_u32 s26, s58, 0x4900
	s_addc_u32 s27, s59, 0
	s_add_u32 s28, s58, 0x4a00
	s_addc_u32 s29, s59, 0
	s_add_u32 s30, s58, 0x4b00
	s_addc_u32 s31, s59, 0
	s_add_u32 s36, s58, 0x4c00
	s_addc_u32 s37, s59, 0
	s_add_u32 s38, s58, 0x4d00
	s_addc_u32 s39, s59, 0
	s_add_u32 s40, s58, 0x4e00
	s_addc_u32 s41, s59, 0
	s_add_u32 s42, s58, 0x4f00
	s_addc_u32 s43, s59, 0
	s_add_u32 s44, s58, 0x5000
	s_addc_u32 s45, s59, 0
	s_add_u32 s46, s58, 0x5100
	s_addc_u32 s47, s59, 0
	s_add_u32 s48, s58, 0x5200
	s_addc_u32 s49, s59, 0
	s_add_u32 s50, s58, 0x5300
	s_mul_i32 s12, s12, s94
	s_addc_u32 s51, s59, 0
	s_mov_b32 s13, 1
	v_mov_b32_e32 v17, 0
	s_branch .LBB0_971

; __device__ __forceinline__ unsigned xb_ld(unsigned* p)              { return __hip_atomic_load(p, __ATOMIC_RELAXED, __HIP_MEMORY_SCOPE_AGENT); }
; __device__ __forceinline__ unsigned xb_add(unsigned* p, unsigned v) { return __hip_atomic_fetch_add(p, v, __ATOMIC_RELAXED, __HIP_MEMORY_SCOPE_AGENT); }
; #define XB_SPIN(cond, bar) do { unsigned _sp = 0; while (cond) { __builtin_amdgcn_s_sleep(1); \
;     if ((++_sp & 255u) == 0u) { if (xb_ld(&(bar)[XB_TMO])) break; if (_sp > XB_SPIN_CAP) { atomicAdd(&(bar)[XB_TMO], 1u); break; } } } } while (0)
; __device__ __forceinline__ void xcd_barrier(const XcdBarrier& b) {
;     asm volatile("s_waitcnt vmcnt(0)" ::: "memory");
;     __syncthreads();
;     if (threadIdx.x == 0) {
;         unsigned* bar = b.bar;
;         __builtin_amdgcn_s_waitcnt(0);
;         unsigned nloc = b.st[0], nx = b.st[1];
;         if (nloc == 0u) { xcd_barrier_complete(bar, b.x, nloc, nx); b.st[0] = nloc; b.st[1] = nx; }
;         const unsigned old = xb_add(&bar[XB_XSUB(b.x)], 1u);
;         const unsigned gen = old / nloc;
;         if (old + 1u == (gen + 1u) * nloc) {
;             __builtin_amdgcn_fence(__ATOMIC_RELEASE, "agent");
;             asm volatile("s_waitcnt vmcnt(0)" ::: "memory");
;             const unsigned og = xb_add(&bar[XB_TOP], 1u);
;             const unsigned tg = og / nx;
;             if (og + 1u == (tg + 1u) * nx) xb_add(&bar[XB_TOPGEN], 1u);
;             else XB_SPIN(xb_ld(&bar[XB_TOPGEN]) == tg, bar);
;             __builtin_amdgcn_fence(__ATOMIC_ACQUIRE, "agent");
;             xb_add(&bar[XB_XGEN(b.x)], 1u);
;             asm volatile("s_waitcnt vmcnt(0)" ::: "memory");
;         } else {
;             XB_SPIN(xb_ld(&bar[XB_XGEN(b.x)]) == gen, bar);
;             __builtin_amdgcn_fence(__ATOMIC_ACQUIRE, "agent");
;             asm volatile("s_waitcnt vmcnt(0)" ::: "memory");
;         }
;     }
;     __syncthreads();
; }
.LBB0_1047:
	s_cmp_gt_i32 s93, 13
	s_cselect_b64 s[0:1], -1, 0
	s_and_b64 s[2:3], s[4:5], s[0:1]
	s_andn2_b64 vcc, exec, s[2:3]
	s_cbranch_vccnz .LBB0_1101
	s_waitcnt vmcnt(0) lgkmcnt(0)
	s_barrier
	s_cmp_lg_u32 s100, 0
	s_cbranch_scc1 .Lxl12_full
	s_and_b32 s6, s14, 7
	s_sub_u32 s7, s94, s6
	s_add_u32 s7, s7, 7
	s_lshr_b32 s7, s7, 3
	s_add_u32 s99, s99, s7
	s_lshl_b32 s6, s6, 8
	s_add_u32 s6, s6, 0x10000
	s_add_u32 s6, s58, s6
	s_addc_u32 s7, s59, 0
	v_readlane_b32 s4, v254, 4
	v_readlane_b32 s5, v254, 5
	s_and_saveexec_b64 s[2:3], s[4:5]
	s_cbranch_execz .Lxl12_join
	v_mov_b32_e32 v1, 0
	v_mov_b32_e32 v2, 1
	global_atomic_add v1, v2, s[6:7]
	s_mov_b32 s8, 0

; __device__ __forceinline__ unsigned xb_ld(unsigned* p)              { return __hip_atomic_load(p, __ATOMIC_RELAXED, __HIP_MEMORY_SCOPE_AGENT); }
; __device__ __forceinline__ unsigned xb_add(unsigned* p, unsigned v) { return __hip_atomic_fetch_add(p, v, __ATOMIC_RELAXED, __HIP_MEMORY_SCOPE_AGENT); }
; #define XB_SPIN(cond, bar) do { unsigned _sp = 0; while (cond) { __builtin_amdgcn_s_sleep(1); \
;     if ((++_sp & 255u) == 0u) { if (xb_ld(&(bar)[XB_TMO])) break; if (_sp > XB_SPIN_CAP) { atomicAdd(&(bar)[XB_TMO], 1u); break; } } } } while (0)
; __device__ __forceinline__ void xcd_barrier(const XcdBarrier& b) {
;     asm volatile("s_waitcnt vmcnt(0)" ::: "memory");
;     __syncthreads();
;     if (threadIdx.x == 0) {
;         unsigned* bar = b.bar;
;         __builtin_amdgcn_s_waitcnt(0);
;         unsigned nloc = b.st[0], nx = b.st[1];
;         if (nloc == 0u) { xcd_barrier_complete(bar, b.x, nloc, nx); b.st[0] = nloc; b.st[1] = nx; }
;         const unsigned old = xb_add(&bar[XB_XSUB(b.x)], 1u);
;         const unsigned gen = old / nloc;
;         if (old + 1u == (gen + 1u) * nloc) {
;             __builtin_amdgcn_fence(__ATOMIC_RELEASE, "agent");
;             asm volatile("s_waitcnt vmcnt(0)" ::: "memory");
;             const unsigned og = xb_add(&bar[XB_TOP], 1u);
;             const unsigned tg = og / nx;
;             if (og + 1u == (tg + 1u) * nx) xb_add(&bar[XB_TOPGEN], 1u);
;             else XB_SPIN(xb_ld(&bar[XB_TOPGEN]) == tg, bar);
;             __builtin_amdgcn_fence(__ATOMIC_ACQUIRE, "agent");
;             xb_add(&bar[XB_XGEN(b.x)], 1u);
;             asm volatile("s_waitcnt vmcnt(0)" ::: "memory");
;         } else {
;             XB_SPIN(xb_ld(&bar[XB_XGEN(b.x)]) == gen, bar);
;             __builtin_amdgcn_fence(__ATOMIC_ACQUIRE, "agent");
;             asm volatile("s_waitcnt vmcnt(0)" ::: "memory");
;         }
;     }
;     __syncthreads();
; }
.LBB0_1128:
	s_cmp_gt_i32 s93, 14
	s_cselect_b64 s[0:1], -1, 0
	s_and_b64 s[2:3], s[4:5], s[0:1]
	s_andn2_b64 vcc, exec, s[2:3]
	s_cbranch_vccnz .LBB0_1182
	s_waitcnt vmcnt(0) lgkmcnt(0)
	s_barrier
	s_cmp_lg_u32 s100, 0
	s_cbranch_scc1 .Lxl13_full
	s_and_b32 s6, s14, 7
	s_sub_u32 s7, s94, s6
	s_add_u32 s7, s7, 7
	s_lshr_b32 s7, s7, 3
	s_add_u32 s99, s99, s7
	s_lshl_b32 s6, s6, 8
	s_add_u32 s6, s6, 0x10000
	s_add_u32 s6, s58, s6
	s_addc_u32 s7, s59, 0
	v_readlane_b32 s4, v254, 4
	v_readlane_b32 s5, v254, 5
	s_and_saveexec_b64 s[2:3], s[4:5]
	s_cbranch_execz .Lxl13_join
	v_mov_b32_e32 v1, 0
	v_mov_b32_e32 v2, 1
	global_atomic_add v1, v2, s[6:7]
	s_mov_b32 s8, 0

; __device__ __forceinline__ unsigned xb_add(unsigned* p, unsigned v) { return __hip_atomic_fetch_add(p, v, __ATOMIC_RELAXED, __HIP_MEMORY_SCOPE_AGENT); }
; __device__ __forceinline__ void xcd_barrier(const XcdBarrier& b) {
;     asm volatile("s_waitcnt vmcnt(0)" ::: "memory");
;     __syncthreads();
;     if (threadIdx.x == 0) {
;         unsigned* bar = b.bar;
;         __builtin_amdgcn_s_waitcnt(0);
;         unsigned nloc = b.st[0], nx = b.st[1];
;         if (nloc == 0u) { xcd_barrier_complete(bar, b.x, nloc, nx); b.st[0] = nloc; b.st[1] = nx; }
;         const unsigned old = xb_add(&bar[XB_XSUB(b.x)], 1u);
;         const unsigned gen = old / nloc;
;         if (old + 1u == (gen + 1u) * nloc) {
.Lxl13_full:
	s_waitcnt vmcnt(0)
	s_waitcnt vmcnt(0)
	s_barrier
	s_mov_b64 s[2:3], exec
	v_readlane_b32 s4, v254, 4
	v_readlane_b32 s5, v254, 5
	s_and_b64 s[4:5], s[2:3], s[4:5]
	s_mov_b64 exec, s[4:5]
	s_cbranch_execz .LBB0_1181
	s_add_i32 s4, 0, 0x20040
	v_mov_b32_e32 v0, s4
	s_waitcnt vmcnt(0) expcnt(0) lgkmcnt(0)
	ds_read_b32 v2, v0
	s_add_i32 s4, 0, 0x20044
	v_mov_b32_e32 v0, s4
	ds_read_b32 v0, v0
	s_waitcnt lgkmcnt(1)
	v_cmp_ne_u32_e32 vcc, 0, v2
	s_cbranch_vccnz .LBB0_1145
	v_readlane_b32 s4, v254, 0
	s_mul_i32 s15, s95, s4
	s_add_u32 s4, s58, 0x4200
	s_addc_u32 s5, s59, 0
	s_add_u32 s6, s58, 0x4400
	s_addc_u32 s7, s59, 0
	s_add_u32 s8, s58, 0x4500
	s_addc_u32 s9, s59, 0
	s_add_u32 s10, s58, 0x4600
	s_addc_u32 s11, s59, 0
	s_add_u32 s12, s58, 0x4700
	s_addc_u32 s13, s59, 0
	s_add_u32 s16, s58, 0x4800
	s_addc_u32 s17, s59, 0
	s_add_u32 s20, s58, 0x4900
	s_addc_u32 s21, s59, 0
	s_add_u32 s24, s58, 0x4a00
	s_addc_u32 s25, s59, 0
	s_add_u32 s26, s58, 0x4b00
	s_addc_u32 s27, s59, 0
	s_add_u32 s28, s58, 0x4c00
	s_addc_u32 s29, s59, 0
	s_add_u32 s30, s58, 0x4d00
	s_addc_u32 s31, s59, 0
	s_add_u32 s36, s58, 0x4e00
	s_addc_u32 s37, s59, 0
	s_add_u32 s38, s58, 0x4f00
	s_addc_u32 s39, s59, 0
	s_add_u32 s40, s58, 0x5000
	s_addc_u32 s41, s59, 0
	s_add_u32 s42, s58, 0x5100
	s_addc_u32 s43, s59, 0
	s_add_u32 s44, s58, 0x5200
	s_addc_u32 s45, s59, 0
	s_add_u32 s46, s58, 0x5300
	s_mul_i32 s15, s15, s94
	s_addc_u32 s47, s59, 0
	s_mov_b32 s33, 1
	v_mov_b32_e32 v16, 0
	s_branch .LBB0_1133

; template <bool FIRST, bool HAS_NEXT, bool CTXSPLIT = false>
; __device__ __forceinline__ void phase_rows(const KArgs& a, int row_begin, int nrows, int CH, const float* mods_cur, int gate_ch, const float* g_post, const float* mods_nxt, int sh_ch, const float* g_pre, int lane, int wave) {
;     ...
;     const int gw = blockIdx.x * NWAVES + wave, NGW = gridDim.x * NWAVES;
;     ...
;     for (int ch = gw; ch < nrows / CH; ch += NGW) {
;         const int r0 = row_begin + ch * CH; const int ms = r0 < MLAT ? r0 / SEQ : 2;
;         f32x4 gg[4], gs[4], sh[4];
; #pragma unroll
;         for (int j = 0; j < 4; ++j) { const int col = RCOL(j);
;             gg[j] = *(const f32x4*)(mods_cur + ms * MODW + gate_ch * DM + col) * *(const f32x4*)(g_post + col);
;             if (HAS_NEXT) { gs[j] = *(const f32x4*)(g_pre + col) * (1.0f + *(const f32x4*)(mods_nxt + ms * MODW + (sh_ch + 1) * DM + col)); sh[j] = *(const f32x4*)(mods_nxt + ms * MODW + sh_ch * DM + col); }
;         }
.LBB0_1182:
	s_cmp_lt_i32 s92, 15
	s_cselect_b64 s[2:3], -1, 0
	s_and_b64 s[0:1], s[2:3], s[0:1]
	s_andn2_b64 vcc, exec, s[0:1]
	s_cbranch_vccnz .LBB0_1186
	s_and_b32 s98, s14, 7
	s_lshl_b32 s98, s98, 5
	s_lshr_b32 s101, s14, 3
	s_or_b32 s98, s98, s101
	s_lshl_b32 s0, s98, 3
	v_readlane_b32 s1, v254, 6
	s_add_i32 s20, s1, s0
	s_cmpk_gt_i32 s20, 0x7ff
	s_cbranch_scc1 .LBB0_1186
	s_lshl_b32 s21, s94, 3
	v_lshlrev_b32_e32 v0, 3, v198
	v_mbcnt_lo_u32_b32 v1, -1, 0
	s_add_u32 s0, s18, 0x1000
	v_mbcnt_hi_u32_b32 v1, -1, v1
	v_mov_b32_e32 v3, 0
	v_or_b32_e32 v4, 0x200, v0
	s_addc_u32 s1, s19, 0
	v_and_b32_e32 v2, 64, v1
	v_lshlrev_b32_e32 v6, 2, v4
	v_mov_b32_e32 v7, v3
	v_add_u32_e32 v5, 64, v2
	v_lshl_add_u64 v[18:19], s[0:1], 0, v[6:7]
	v_xor_b32_e32 v6, 1, v1
	v_cmp_lt_i32_e32 vcc, v6, v5
	v_lshlrev_b32_e32 v2, 5, v198
	v_lshl_add_u64 v[16:17], s[0:1], 0, v[2:3]
	v_cndmask_b32_e32 v6, v1, v6, vcc
	v_lshlrev_b32_e32 v66, 2, v6
	v_xor_b32_e32 v6, 2, v1
	v_cmp_lt_i32_e32 vcc, v6, v5
	s_mov_b64 s[0:1], 0xd000000
	v_lshl_add_u64 v[24:25], s[56:57], 0, v[2:3]
	v_cndmask_b32_e32 v6, v1, v6, vcc
	v_lshlrev_b32_e32 v67, 2, v6
	v_xor_b32_e32 v6, 4, v1
	v_cmp_lt_i32_e32 vcc, v6, v5
	s_lshl_b32 s18, s94, 6
	v_lshlrev_b32_e32 v72, 2, v0
	v_cndmask_b32_e32 v6, v1, v6, vcc
	v_lshlrev_b32_e32 v68, 2, v6
	v_xor_b32_e32 v6, 8, v1
	v_cmp_lt_i32_e32 vcc, v6, v5
	v_lshlrev_b32_e32 v73, 2, v4
	v_mov_b32_e32 v74, 0x358637bd
	v_cndmask_b32_e32 v6, v1, v6, vcc
	v_lshlrev_b32_e32 v69, 2, v6
	v_xor_b32_e32 v6, 16, v1
	v_cmp_lt_i32_e32 vcc, v6, v5
	s_mov_b32 s19, 0xf800000
	v_mov_b32_e32 v75, 0x260
	v_cndmask_b32_e32 v6, v1, v6, vcc
	v_lshlrev_b32_e32 v70, 2, v6
	v_xor_b32_e32 v6, 32, v1
	v_cmp_lt_i32_e32 vcc, v6, v5
	s_nop 1
	v_cndmask_b32_e32 v1, v1, v6, vcc
	v_lshlrev_b32_e32 v6, 4, v198
	v_lshl_add_u64 v[8:9], s[58:59], 0, v[6:7]
	v_lshl_add_u64 v[20:21], v[8:9], 0, s[0:1]
	v_readlane_b32 s1, v254, 6
	s_lshl_b32 s0, s98, 6
	s_lshl_b32 s1, s1, 3
	s_add_i32 s0, s0, s1
	v_lshlrev_b32_e32 v71, 2, v1
	v_lshl_add_u64 v[22:23], s[22:23], 0, v[6:7]
	s_or_b32 s6, s0, 7
